# attention work order (8 workgroups per seq-head stream, query blocks 15-p then p) and load-pipelined out-projection epilogue stacked on the previous version
# speedup vs baseline: 1.0589x; 1.0058x over previous
; template <int VAR> __device__ __forceinline__ void attn_phase(LAS unsigned char* lds, const PTab& P, const int wid_s) {
;     ...
;     for (int it = 0; it < rounds; ++it) {
;         int hh, ntiles, mylast, qrow, kroff, len;
;         if (xcd_order) {
;             const int x = c & 7, j = c >> 3;
;             if (it < 8) {
;                 hh = (it & 1) ? 4 + (it >> 1) : (it >> 1);
;                 const int seq = 2 * x + (j >> 4), qb = ((it >> 1) & 1) ? 15 - (j & 15) : (j & 15);
;                 ntiles = 4 * qb + 4; mylast = 4 * qb + (wave >> 1); qrow = seq * 4096 + qb * 256 + 32 * wave + r; kroff = seq * 4096; len = SEQ;
.LBB0_719:
	s_cmp_lt_i32 s40, 1
	s_cbranch_scc1 .LBB0_867
	s_ashr_i32 s12, s3, 6
	s_add_u32 s6, s16, 0x99e5800
	s_addc_u32 s7, s14, 0
	s_add_u32 s41, s16, 0xda65800
	s_addc_u32 s42, s14, 0
	s_add_u32 s43, s16, 0x122e5800
	s_addc_u32 s44, s14, 0
	s_add_u32 s8, s16, 0x1fe85800
	s_addc_u32 s9, s14, 0
	s_add_u32 s45, s16, 0x25f45800
	s_addc_u32 s46, s14, 0
	s_add_u32 s47, s16, 0x2cc05800
	s_addc_u32 s48, s14, 0
	s_add_u32 s10, s16, 0x18e5800
	s_waitcnt lgkmcnt(1)
	v_add_f32_e32 v1, v1, v2
	s_waitcnt lgkmcnt(0)
	v_add_f32_e32 v2, v3, v4
	s_addc_u32 s11, s14, 0
	s_not_b32 s13, s2
	v_mul_f32_e32 v1, 0x3fb8aa3b, v1
	v_mul_f32_e32 v2, 0x3fb8aa3b, v2
	s_add_i32 s49, s33, s13
	v_exp_f32_e32 v1, v1
	v_exp_f32_e32 v2, v2
	s_cmp_lt_i32 s12, 2
	s_cselect_b32 s50, 16, -1
	s_lshl_b32 s51, s12, 5
	s_and_b32 s53, s51, 32
	s_bitset1_b32 s53, 16
	s_ashr_i32 s54, s3, 7
	s_and_b32 s3, s2, 7
	s_ashr_i32 s55, s2, 3
	v_and_b32_e32 v227, 31, v0
	v_sub_f32_e32 v1, v1, v2
	s_cmp_lt_i32 s55, 8
	v_add_f32_e32 v202, 0x3e4ccccd, v1
	s_cselect_b64 s[12:13], -1, 0
	v_lshl_or_b32 v1, s3, 6, v227
	s_mul_i32 s56, s3, 0x440
	s_lshl_b32 s59, s3, 13
	s_lshl_b32 s3, s2, 6
	s_and_b32 s3, s3, 0x1000
	s_mov_b32 s15, 0
	s_and_b32 s57, s55, 7
	s_add_i32 s59, s59, s3
	s_mov_b32 s3, s15
	s_bitset1_b32 s56, 16
	s_xor_b32 s58, s57, 15
	s_lshl_b64 s[20:21], s[2:3], 17
	v_or_b32_e32 v228, s53, v1
	v_or_b32_e32 v1, s59, v227
	v_lshrrev_b32_e32 v0, 3, v0
	v_ashrrev_i32_e32 v201, 31, v200
	s_add_u32 s16, s16, s20
	v_add_u32_e32 v229, s51, v1
	v_and_b32_e32 v204, 4, v0
	s_addc_u32 s17, s14, s21
	v_lshlrev_b64 v[0:1], 8, v[200:201]
	v_lshl_add_u64 v[0:1], s[16:17], 0, v[0:1]
	s_mov_b64 s[16:17], 0x31485800
	v_lshl_add_u64 v[206:207], v[0:1], 0, s[16:17]
	v_mov_b32_e32 v1, 0
	v_lshlrev_b32_e32 v0, 2, v204
	s_mov_b32 s52, 0x10000
	v_lshl_add_u64 v[208:209], s[0:1], 0, v[0:1]
	v_mov_b32_e32 v203, v202
	s_movk_i32 s3, 0x600
	s_movk_i32 s60, 0x90
	s_mov_b32 s61, 0x2aaaaaab
	s_movk_i32 s62, 0x190
	v_mov_b32_e32 v201, 0x358637bd
	s_mov_b32 s63, 0x800000
	s_mov_b32 s64, 0
	s_branch .LBB0_722

; template <int VAR> __device__ __forceinline__ void attn_phase(LAS unsigned char* lds, const PTab& P, const int wid_s) {
;     ...
;         if (xcd_order) {
;             const int x = c & 7, j = c >> 3;
;             if (it < 8) {
;                 hh = (it & 1) ? 4 + (it >> 1) : (it >> 1);
;                 const int seq = 2 * x + (j >> 4), qb = ((it >> 1) & 1) ? 15 - (j & 15) : (j & 15);
;                 ntiles = 4 * qb + 4; mylast = 4 * qb + (wave >> 1); qrow = seq * 4096 + qb * 256 + 32 * wave + r; kroff = seq * 4096; len = SEQ;
.LBB0_736:
	s_andn2_b64 vcc, exec, s[16:17]
	s_cbranch_vccnz .LBB0_738
	s_lshr_b32 s0, s64, 1
	s_lshr_b32 s1, s2, 7
	s_and_b32 s14, s0, 1
	s_xor_b32 s14, s14, s1
	s_lshl_b32 s14, s14, 2
	s_lshr_b32 s0, s0, 1
	s_add_i32 s14, s14, s0
	s_lshl_b32 s1, s1, 1
	s_add_i32 s14, s14, s1
	s_bitcmp0_b32 s64, 0
	s_cselect_b32 s0, s58, s57
	s_lshl_b32 s1, s0, 2
	s_add_i32 s22, s1, 4
	s_add_i32 s23, s1, s54
	v_lshl_add_u32 v0, s0, 8, v229
	s_mov_b64 s[0:1], -1
	s_movk_i32 s24, 0x1000
	s_mov_b32 s25, s59
